# ffn-down GEMM: split-K factor of the tail tiles 8 -> 4 (on top of out-proj 8 -> 4)
# baseline (speedup 1.0000x reference)
;   if (ph == 0) { phase0(p, smem); return; }
;   const int layer = (ph - 1) / PH_PER_LAYER, sub = (ph - 1) % PH_PER_LAYER;
;   const int kind = layer % 3, j = layer / 3;
;   const bool last = layer == 3;
;   const float* modsL = (const float*)(p.ws + OFF_MODS) + (size_t)layer * 5 * 6144;
;   const bf16_t* abuf = (const bf16_t*)(p.ws + OFF_ABUF);
;   char* mix = p.ws + OFF_MIX;
;   switch (sub) {
;     case 0:
;       phase_norm(p, p.in[6] + layer * DM, modsL, 0, 1, false);
;       phase_convert(p, layer);
;       break;
;     case 1:
;       if (kind == 0) { EpiMlaIn e{(float*)(p.ws + MLA_Q)}; gemm_phase<2, false>(abuf, (const bf16_t*)mix, 1024, 3, false, e, smem); }
;       else if (kind == 1) { EpiHgIn e{p.ws}; gemm_phase_pref<2, false>(abuf, (const bf16_t*)mix, 1024, 20, false, e, smem); }
;       else { EpiDfQkv e{p.ws, p.in[26], p.in[27]}; gemm_phase<2, true>(abuf, (const bf16_t*)mix, 1024, 12, false, e, smem); }
;       break;
;     case 2:
;       if (kind == 0) phase_mla_post(p, j);
;       else if (kind == 1) phase_hg_scan(p, smem);
;       else phase_attn_df(p, !last, smem);
;       break;
;     case 3:
;       if (kind == 0) {
;         EpiMlaUq e1{p.ws, p.in[16] + j * 128, p.in[17] + j * 64};
;         gemm_phase<2, true>((const bf16_t*)(p.ws + MLA_CQN), (const bf16_t*)(mix + 1572864), 384, 6, false, e1, smem);
;         EpiMlaUkv e2{p.ws, p.in[18] + j * 128};
;         gemm_phase<2, true>((const bf16_t*)(p.ws + MLA_CKVN), (const bf16_t*)(mix + 2752512), 256, 8, false, e2, smem);
;       } else if (kind == 1) phase_hg_readout(p, j);
;       break;
;     case 4:
;       if (kind == 0) phase_attn_mla(p, !last, smem);
;       break;
;     case 5: {
;       EpiX e{&p, modsL + 2 * 1024, rep ? 0.f : 1.f};
;       const bf16_t* wo = (const bf16_t*)(mix + (kind == 0 ? 3801088 : kind == 1 ? 10485760 : 6291456));
;       gemm_phase<2, false, 8>(abuf, wo, 1024, 4, last, e, smem);
;     } break;
;     case 6:
;       phase_norm(p, p.in[7] + layer * DM, modsL, 3, 4, last);
;       break;
;     case 7: {
;       EpiFfnUp e{(bf16_t*)(p.ws + FFN_H)};
;       gemm_phase_pref<2, false>(abuf, (const bf16_t*)(p.ws + OFF_W13), 1024, 22, last, e, smem);
;     } break;
;     case 8: {
;       EpiX e{&p, modsL + 5 * 1024, rep ? 0.f : 1.f};
;       gemm_phase<2, false, 8>((const bf16_t*)(p.ws + FFN_H), (const bf16_t*)(p.ws + OFF_W2), DFF, 4, last, e, smem);
.LBB0_11:
	s_add_i32 s44, s22, -1
	s_mul_hi_i32 s0, s44, 0x38e38e39
	s_lshr_b32 s1, s0, 31
	s_ashr_i32 s0, s0, 1
	s_add_i32 s30, s0, s1
	s_mul_i32 s0, s30, 9
	s_sub_i32 s31, s44, s0
	s_mul_hi_i32 s0, s30, 0x55555556
	s_lshr_b32 s1, s0, 31
	s_add_i32 s0, s0, s1
	s_mul_i32 s0, s0, 3
	s_sub_i32 s3, s30, s0
	s_cmp_eq_u32 s31, 4
	s_cselect_b64 s[0:1], -1, 0
	s_cmp_lg_u32 s3, 0
	s_cselect_b64 s[24:25], -1, 0
	s_and_b64 s[0:1], s[0:1], s[24:25]
	s_cmp_eq_u32 s31, 3
	s_cselect_b64 s[24:25], -1, 0
	s_cmp_eq_u32 s3, 2
	s_cselect_b64 s[28:29], -1, 0
	s_and_b64 s[24:25], s[24:25], s[28:29]
	s_or_b64 s[0:1], s[0:1], s[24:25]
	s_andn2_b64 vcc, exec, s[0:1]
	s_cbranch_vccz .LBB0_19
	s_sub_i32 s0, s22, 28
	s_cmp_lt_u32 s0, 9
	s_cselect_b64 s[40:41], -1, 0
	s_cmp_gt_u32 s0, 8
	s_cselect_b64 s[0:1], -1, 0
	v_writelane_b32 v254, s0, 63
	s_mov_b32 s12, s3
	v_readlane_b32 s24, v254, 61
	v_writelane_b32 v255, s1, 0
	s_mul_i32 s0, s30, 5
	s_mul_i32 s1, s30, 0x1e000
	s_mul_hi_i32 s0, s0, 0x6000
	v_readlane_b32 s25, v254, 62
	s_add_u32 s24, s24, s1
	v_writelane_b32 v255, s30, 1
	s_addc_u32 s25, s25, s0
	v_writelane_b32 v255, s24, 2
	s_mov_b32 s9, s31
	s_cmp_lt_i32 s31, 4
	v_writelane_b32 v255, s25, 3
	s_mov_b64 s[0:1], -1
	s_cbranch_scc1 .LBB0_134
	s_cmp_lt_i32 s9, 6
	s_cbranch_scc1 .LBB0_94
	s_cmp_lt_i32 s9, 7
	s_cbranch_scc1 .LBB0_76
	s_cmp_lt_i32 s9, 8
	s_cbranch_scc1 .LBB0_43
	s_cmp_eq_u32 s9, 8
	s_cbranch_scc0 .LBB0_42
	s_waitcnt vmcnt(1)
	v_mov_b32_e32 v0, v167
	s_mov_b32 s0, s50
	s_and_b32 s3, s0, 7
	s_mov_b32 s0, s50
	s_ashr_i32 s45, s0, 3
	s_sub_i32 s0, 0x8b, s3
	s_lshr_b32 s0, s0, 1
	s_and_b32 s0, s0, 0x44
	v_readlane_b32 s1, v253, 59
	s_mul_hi_u32 s1, s0, s1
	v_readlane_b32 s24, v254, 7
	s_mul_i32 s1, s1, s24
	s_sub_i32 s1, s0, s1
	s_mov_b32 s28, s24
	s_sub_i32 s24, s1, s24
	s_cmp_ge_u32 s1, s28
	s_cselect_b32 s1, s24, s1
	s_sub_i32 s24, s1, s28
	s_cmp_ge_u32 s1, s28
	s_cselect_b32 s1, s24, s1
	s_sub_i32 s46, s0, s1
	s_lshl_b32 s0, s1, 2
	s_add_i32 s47, s46, s0
	s_cmp_ge_i32 s45, s47
	v_readlane_b32 s25, v254, 8
	s_cbranch_scc1 .LBB0_42
	v_readlane_b32 s0, v255, 2
	v_readlane_b32 s1, v255, 3
	s_add_u32 s48, s0, 0x5000
	v_ashrrev_i32_e32 v1, 3, v0
	v_mov_b64_e32 v[2:3], s[52:53]
	s_movk_i32 s24, 0x1600
	s_addc_u32 s49, s1, 0
	v_mad_i64_i32 v[2:3], s[0:1], v1, s24, v[2:3]
	v_lshlrev_b32_e32 v4, 4, v0
	v_readlane_b32 s0, v252, 6
	v_and_b32_e32 v140, 0x70, v4
	v_readlane_b32 s1, v252, 7
	s_waitcnt vmcnt(0)
	v_lshl_add_u64 v[162:163], v[2:3], 0, v[140:141]
	v_ashrrev_i32_e32 v169, 8, v0
	v_mov_b64_e32 v[2:3], s[0:1]
	v_mad_i64_i32 v[2:3], s[0:1], v1, s24, v[2:3]
	s_movk_i32 s0, 0x90
	s_nop 0
	v_mul_lo_u32 v1, v1, s0
	v_add3_u32 v188, 0, v1, v140
	v_and_b32_e32 v1, 0xdf, v0
	v_and_b32_e32 v187, 31, v0
	v_mul_u32_u24_e32 v189, 0x90, v1
	v_lshrrev_b32_e32 v1, 1, v0
	v_and_b32_e32 v190, 16, v1
	v_lshl_or_b32 v1, v169, 7, v187
	v_and_b32_e32 v186, 0xc0, v0
	v_mul_lo_u32 v1, v1, s0
	v_lshlrev_b32_e32 v0, 7, v0
	s_movk_i32 s0, 0x1000
	s_movk_i32 s34, 0x2000
	v_lshl_add_u64 v[164:165], v[2:3], 0, v[140:141]
	v_add_u32_e32 v191, 0x9000, v1
	v_and_or_b32 v168, v0, s0, v187
	s_branch .LBB0_21

; #define SSTOREG(buf_) do { char* b_ = (buf_) + lo; \
;       *(uint4*)(b_) = ra0; *(uint4*)(b_ + 64 * GSTR) = ra1; *(uint4*)(b_ + 128 * GSTR) = ra2; *(uint4*)(b_ + 192 * GSTR) = ra3; \
;       *(uint4*)(b_ + 256 * GSTR) = rw0; *(uint4*)(b_ + 320 * GSTR) = rw1; \
;       if (WM == 2) { *(uint4*)(b_ + 384 * GSTR) = rw2; *(uint4*)(b_ + 448 * GSTR) = rw3; } } while (0)
; #define SSTOREG(buf_) do { char* b_ = (buf_) + lo; \
;       *(uint4*)(b_) = ra0; *(uint4*)(b_ + 64 * GSTR) = ra1; *(uint4*)(b_ + 128 * GSTR) = ra2; *(uint4*)(b_ + 192 * GSTR) = ra3; \
;       *(uint4*)(b_ + 256 * GSTR) = rw0; *(uint4*)(b_ + 320 * GSTR) = rw1; \
;       if (WM == 2) { *(uint4*)(b_ + 384 * GSTR) = rw2; *(uint4*)(b_ + 448 * GSTR) = rw3; } } while (0)
;     ...
;   for (int u = slot; u < nunits; u += nslots) {
;     const bool part = u >= full;
;     const int q = part ? full + (u - full) / NSP : u, ks = part ? (u - full) % NSP : 0;
;     const int mtl = q / ntiles, nt = q - mtl * ntiles, mt = mtl * 8 + xcd;
;     if (skipctx && (mt % PT) == 0) continue;
;     const int kt0 = part ? (ks * nk) / NSP : 0, kt1 = part ? ((ks + 1) * nk) / NSP : nk;
;     const bf16_t* Ag = A + (size_t)mt * 256 * K;
;     const bf16_t* Wg = W + (size_t)nt * BN * K;
;     f32x16 acc[WM][4];
; #pragma unroll
;     for (int mi = 0; mi < WM; ++mi)
; #pragma unroll
;       for (int nb = 0; nb < 4; ++nb)
; #pragma unroll
;         for (int i = 0; i < 16; ++i) acc[mi][nb][i] = 0.f;
;     uint4 ra0, ra1, ra2, ra3, rw0, rw1, rw2, rw3;
;     rw2 = make_uint4(0, 0, 0, 0); rw3 = rw2;
;     const int grow = tid >> 3, gcol = (tid & 7) * 8;
;     const bf16_t* ap = Ag + (size_t)grow * K + gcol;
;     const bf16_t* wp = Wg + (size_t)grow * K + gcol;
;     const int lo = grow * GSTR + (tid & 7) * 16;
;     ...
;     GLOADG(kt0); SSTOREG(smem);
.LBB0_21:
	s_cmp_ge_i32 s45, s46
	s_cselect_b64 s[0:1], -1, 0
	s_sub_i32 s24, s45, s46
	s_lshr_b32 s25, s24, 2
	s_add_i32 s25, s25, s46
	s_cmp_lt_i32 s45, s46
	s_cselect_b64 s[28:29], -1, 0
	s_and_b64 s[30:31], s[28:29], exec
	s_cselect_b32 s25, s45, s25
	s_ashr_i32 s27, s25, 31
	s_lshr_b32 s27, s27, 30
	s_add_i32 s27, s25, s27
	s_ashr_i32 s27, s27, 2
	s_lshl_b32 s30, s27, 3
	s_or_b32 s30, s30, s3
	s_mul_hi_i32 s31, s30, 0x3e0f83e1
	s_lshr_b32 s36, s31, 31
	s_ashr_i32 s31, s31, 3
	s_add_i32 s31, s31, s36
	s_mul_i32 s31, s31, 33
	s_sub_i32 s31, s30, s31
	s_cmp_eq_u32 s31, 0
	s_cselect_b64 s[36:37], -1, 0
	s_and_b64 s[36:37], s[40:41], s[36:37]
	s_and_b64 vcc, exec, s[36:37]
	s_cbranch_vccnz .LBB0_20
	s_and_b32 s24, s24, 3
	s_lshl_b32 s27, s27, 2
	s_mul_i32 s24, s24, 44
	s_sub_i32 s31, s25, s27
	s_lshr_b32 s27, s24, 2
	s_add_i32 s24, s24, 44
	s_lshr_b32 s36, s24, 2
	v_mov_b32_e32 v0, 0x160000
	s_and_b64 s[24:25], s[28:29], exec
	v_mad_i64_i32 v[170:171], s[24:25], s30, v0, v[162:163]
	v_mad_i64_i32 v[172:173], s[24:25], s31, v0, v[164:165]
	s_cselect_b32 s28, 0, s27
	s_mov_b64 s[24:25], 0x58000
	s_cselect_b32 s29, 44, s36
	s_lshl_b32 s96, s28, 7
	v_lshl_add_u64 v[174:175], v[170:171], 0, s[24:25]
	s_waitcnt vmcnt(6)
	v_lshl_add_u64 v[180:181], v[172:173], 0, s[24:25]
	s_add_i32 s24, s28, 1
	s_mov_b64 s[36:37], 0xb0000
	s_mov_b64 s[38:39], 0x108000
	s_cmp_lt_u32 s24, s29
	v_lshl_add_u64 v[176:177], v[170:171], 0, s[36:37]
	s_waitcnt vmcnt(4)
	v_lshl_add_u64 v[178:179], v[170:171], 0, s[38:39]
	v_lshl_add_u64 v[182:183], v[172:173], 0, s[36:37]
	v_lshl_add_u64 v[184:185], v[172:173], 0, s[38:39]
	s_cselect_b32 s24, s24, s28
	v_lshl_add_u64 v[0:1], v[170:171], 0, s[96:97]
	v_lshl_add_u64 v[4:5], v[174:175], 0, s[96:97]
	v_lshl_add_u64 v[8:9], v[176:177], 0, s[96:97]
	v_lshl_add_u64 v[12:13], v[178:179], 0, s[96:97]
	v_lshl_add_u64 v[16:17], v[172:173], 0, s[96:97]
	v_lshl_add_u64 v[20:21], v[180:181], 0, s[96:97]
	v_lshl_add_u64 v[24:25], v[182:183], 0, s[96:97]
	v_lshl_add_u64 v[28:29], v[184:185], 0, s[96:97]
	s_lshl_b32 s96, s24, 7
	v_lshl_add_u64 v[32:33], v[170:171], 0, s[96:97]
	global_load_dwordx4 v[0:3], v[0:1], off
	s_nop 0
	global_load_dwordx4 v[4:7], v[4:5], off
	s_nop 0
	global_load_dwordx4 v[8:11], v[8:9], off
	s_nop 0
	global_load_dwordx4 v[12:15], v[12:13], off
	s_nop 0
	global_load_dwordx4 v[16:19], v[16:17], off
	s_nop 0
	global_load_dwordx4 v[20:23], v[20:21], off
	s_nop 0
	global_load_dwordx4 v[24:27], v[24:25], off
	s_nop 0
	global_load_dwordx4 v[28:31], v[28:29], off
	v_lshl_add_u64 v[34:35], v[174:175], 0, s[96:97]
	v_lshl_add_u64 v[36:37], v[176:177], 0, s[96:97]
	v_lshl_add_u64 v[38:39], v[178:179], 0, s[96:97]
	v_lshl_add_u64 v[40:41], v[172:173], 0, s[96:97]
	v_lshl_add_u64 v[42:43], v[180:181], 0, s[96:97]
	v_lshl_add_u64 v[44:45], v[182:183], 0, s[96:97]
	v_lshl_add_u64 v[46:47], v[184:185], 0, s[96:97]
	global_load_dwordx4 v[158:161], v[32:33], off
	global_load_dwordx4 v[154:157], v[34:35], off
	global_load_dwordx4 v[150:153], v[36:37], off
	global_load_dwordx4 v[146:149], v[38:39], off
	global_load_dwordx4 v[142:145], v[40:41], off
	global_load_dwordx4 v[136:139], v[42:43], off
	global_load_dwordx4 v[132:135], v[44:45], off
	global_load_dwordx4 v[128:131], v[46:47], off
	v_mov_b32_e32 v127, 0
	v_mov_b32_e32 v126, v127
	v_mov_b32_e32 v125, v127
	v_mov_b32_e32 v124, v127
	v_mov_b32_e32 v123, v127
	v_mov_b32_e32 v122, v127
	v_mov_b32_e32 v121, v127
	v_mov_b32_e32 v120, v127
	v_mov_b32_e32 v119, v127
	v_mov_b32_e32 v118, v127
	v_mov_b32_e32 v117, v127
	v_mov_b32_e32 v116, v127
	v_mov_b32_e32 v115, v127
	v_mov_b32_e32 v114, v127
	v_mov_b32_e32 v113, v127
	v_mov_b32_e32 v112, v127
	v_mov_b32_e32 v111, v127
	v_mov_b32_e32 v110, v127
	v_mov_b32_e32 v109, v127
	v_mov_b32_e32 v108, v127
	s_cmp_ge_u32 s28, s29
	v_mov_b32_e32 v107, v127
	v_mov_b32_e32 v106, v127
	s_waitcnt vmcnt(19)
	v_mov_b32_e32 v105, v127
	s_waitcnt vmcnt(18)
	v_mov_b32_e32 v104, v127
	s_waitcnt vmcnt(17)
	v_mov_b32_e32 v103, v127
	s_waitcnt vmcnt(16)
	v_mov_b32_e32 v102, v127
	v_mov_b32_e32 v101, v127
	v_mov_b32_e32 v100, v127
	v_mov_b32_e32 v99, v127
	v_mov_b32_e32 v98, v127
	v_mov_b32_e32 v97, v127
	v_mov_b32_e32 v96, v127
	v_mov_b32_e32 v95, v127
	v_mov_b32_e32 v94, v127
	v_mov_b32_e32 v93, v127
	v_mov_b32_e32 v92, v127
	v_mov_b32_e32 v91, v127
	s_waitcnt vmcnt(15)
	ds_write_b128 v188, v[0:3]
	s_waitcnt vmcnt(14)
	ds_write_b128 v188, v[4:7] offset:9216
	s_waitcnt vmcnt(13)
	ds_write_b128 v188, v[8:11] offset:18432
	s_waitcnt vmcnt(12)
	ds_write_b128 v188, v[12:15] offset:27648
	s_waitcnt vmcnt(11)
	ds_write_b128 v188, v[16:19] offset:36864
	s_waitcnt vmcnt(10)
	ds_write_b128 v188, v[20:23] offset:46080
	s_waitcnt vmcnt(9)
	ds_write_b128 v188, v[24:27] offset:55296
	s_waitcnt vmcnt(8)
; #define SSTOREG(buf_) do { char* b_ = (buf_) + lo; \
;       *(uint4*)(b_) = ra0; *(uint4*)(b_ + 64 * GSTR) = ra1; *(uint4*)(b_ + 128 * GSTR) = ra2; *(uint4*)(b_ + 192 * GSTR) = ra3; \
;       *(uint4*)(b_ + 256 * GSTR) = rw0; *(uint4*)(b_ + 320 * GSTR) = rw1; \
;       if (WM == 2) { *(uint4*)(b_ + 384 * GSTR) = rw2; *(uint4*)(b_ + 448 * GSTR) = rw3; } } while (0)
; #define SSTOREG(buf_) do { char* b_ = (buf_) + lo; \
;       *(uint4*)(b_) = ra0; *(uint4*)(b_ + 64 * GSTR) = ra1; *(uint4*)(b_ + 128 * GSTR) = ra2; *(uint4*)(b_ + 192 * GSTR) = ra3; \
;       *(uint4*)(b_ + 256 * GSTR) = rw0; *(uint4*)(b_ + 320 * GSTR) = rw1; \
;       if (WM == 2) { *(uint4*)(b_ + 384 * GSTR) = rw2; *(uint4*)(b_ + 448 * GSTR) = rw3; } } while (0)
;     ...
;     f32x16 acc[WM][4];
; #pragma unroll
;     for (int mi = 0; mi < WM; ++mi)
; #pragma unroll
;       for (int nb = 0; nb < 4; ++nb)
; #pragma unroll
;         for (int i = 0; i < 16; ++i) acc[mi][nb][i] = 0.f;
;     uint4 ra0, ra1, ra2, ra3, rw0, rw1, rw2, rw3;
;     rw2 = make_uint4(0, 0, 0, 0); rw3 = rw2;
;     const int grow = tid >> 3, gcol = (tid & 7) * 8;
;     const bf16_t* ap = Ag + (size_t)grow * K + gcol;
;     const bf16_t* wp = Wg + (size_t)grow * K + gcol;
;     const int lo = grow * GSTR + (tid & 7) * 16;
;     ...
;     GLOADG(kt0); SSTOREG(smem);
;     if (WM == 2) GLOADG(kt0 + 1 < kt1 ? kt0 + 1 : kt0);
;     __syncthreads();
;     for (int kt = kt0; kt < kt1; ++kt) {
	ds_write_b128 v188, v[28:31] offset:64512
	v_mov_b32_e32 v90, v127
	v_mov_b32_e32 v89, v127
	v_mov_b32_e32 v88, v127
	v_mov_b32_e32 v87, v127
	v_mov_b32_e32 v86, v127
	v_mov_b32_e32 v85, v127
	v_mov_b32_e32 v84, v127
	v_mov_b32_e32 v83, v127
	v_mov_b32_e32 v82, v127
	v_mov_b32_e32 v81, v127
	v_mov_b32_e32 v80, v127
	v_mov_b32_e32 v79, v127
	v_mov_b32_e32 v78, v127
	v_mov_b32_e32 v77, v127
	v_mov_b32_e32 v76, v127
	v_mov_b32_e32 v75, v127
	v_mov_b32_e32 v74, v127
	v_mov_b32_e32 v73, v127
	v_mov_b32_e32 v72, v127
	v_mov_b32_e32 v71, v127
	v_mov_b32_e32 v70, v127
	v_mov_b32_e32 v69, v127
	v_mov_b32_e32 v68, v127
	v_mov_b32_e32 v67, v127
	v_mov_b32_e32 v66, v127
	v_mov_b32_e32 v65, v127
	v_mov_b32_e32 v64, v127
	v_mov_b32_e32 v63, v127
	v_mov_b32_e32 v62, v127
	v_mov_b32_e32 v61, v127
	v_mov_b32_e32 v60, v127
	v_mov_b32_e32 v59, v127
	v_mov_b32_e32 v58, v127
	v_mov_b32_e32 v57, v127
	v_mov_b32_e32 v56, v127
	v_mov_b32_e32 v55, v127
	v_mov_b32_e32 v54, v127
	v_mov_b32_e32 v53, v127
	v_mov_b32_e32 v52, v127
	v_mov_b32_e32 v51, v127
	v_mov_b32_e32 v50, v127
	v_mov_b32_e32 v49, v127
	v_mov_b32_e32 v48, v127
	v_mov_b32_e32 v47, v127
	v_mov_b32_e32 v46, v127
	v_mov_b32_e32 v45, v127
	v_mov_b32_e32 v44, v127
	v_mov_b32_e32 v43, v127
	v_mov_b32_e32 v42, v127
	v_mov_b32_e32 v41, v127
	v_mov_b32_e32 v40, v127
	v_mov_b32_e32 v39, v127
	v_mov_b32_e32 v38, v127
	v_mov_b32_e32 v37, v127
	v_mov_b32_e32 v36, v127
	v_mov_b32_e32 v35, v127
	v_mov_b32_e32 v34, v127
	v_mov_b32_e32 v33, v127
	v_mov_b32_e32 v32, v127
	v_mov_b32_e32 v31, v127
	v_mov_b32_e32 v30, v127
	v_mov_b32_e32 v29, v127
	v_mov_b32_e32 v28, v127
	v_mov_b32_e32 v27, v127
	v_mov_b32_e32 v26, v127
	v_mov_b32_e32 v25, v127
	v_mov_b32_e32 v24, v127
	v_mov_b32_e32 v23, v127
	v_mov_b32_e32 v22, v127
	v_mov_b32_e32 v21, v127
	v_mov_b32_e32 v20, v127
	v_mov_b32_e32 v19, v127
	v_mov_b32_e32 v18, v127
	v_mov_b32_e32 v17, v127
	v_mov_b32_e32 v16, v127
	v_mov_b32_e32 v15, v127
	v_mov_b32_e32 v14, v127
	v_mov_b32_e32 v13, v127
	v_mov_b32_e32 v12, v127
	v_mov_b32_e32 v11, v127
	v_mov_b32_e32 v10, v127
	v_mov_b32_e32 v9, v127
	v_mov_b32_e32 v8, v127
	v_mov_b32_e32 v7, v127
	v_mov_b32_e32 v6, v127
	v_mov_b32_e32 v5, v127
	v_mov_b32_e32 v4, v127
	v_mov_b32_e32 v3, v127
	v_mov_b32_e32 v2, v127
	v_mov_b32_e32 v1, v127
	v_mov_b32_e32 v0, v127
	s_waitcnt lgkmcnt(0)
	s_barrier
	s_cbranch_scc1 .LBB0_25
	v_mov_b32_e32 v0, 0
	s_mov_b32 s27, 0
	v_mov_b32_e32 v1, v0
	v_mov_b32_e32 v2, v0
	v_mov_b32_e32 v3, v0
	v_mov_b32_e32 v4, v0
	v_mov_b32_e32 v5, v0
	v_mov_b32_e32 v6, v0
	v_mov_b32_e32 v7, v0
	v_mov_b32_e32 v8, v0
	v_mov_b32_e32 v9, v0
	v_mov_b32_e32 v10, v0
	v_mov_b32_e32 v11, v0
	v_mov_b32_e32 v12, v0
	v_mov_b32_e32 v13, v0
	v_mov_b32_e32 v14, v0
	v_mov_b32_e32 v15, v0
	v_mov_b32_e32 v16, v0
	v_mov_b32_e32 v17, v0
	v_mov_b32_e32 v18, v0
	v_mov_b32_e32 v19, v0
	v_mov_b32_e32 v20, v0
	v_mov_b32_e32 v21, v0
	v_mov_b32_e32 v22, v0
	v_mov_b32_e32 v23, v0
	v_mov_b32_e32 v24, v0
	v_mov_b32_e32 v25, v0
	v_mov_b32_e32 v26, v0
	v_mov_b32_e32 v27, v0
	v_mov_b32_e32 v28, v0
	v_mov_b32_e32 v29, v0
	v_mov_b32_e32 v30, v0
	v_mov_b32_e32 v31, v0
	v_mov_b32_e32 v32, v0
	v_mov_b32_e32 v33, v0
	v_mov_b32_e32 v34, v0
	v_mov_b32_e32 v35, v0
	v_mov_b32_e32 v36, v0
	v_mov_b32_e32 v37, v0
	v_mov_b32_e32 v38, v0
	v_mov_b32_e32 v39, v0
	v_mov_b32_e32 v40, v0
	v_mov_b32_e32 v41, v0
	v_mov_b32_e32 v42, v0
	v_mov_b32_e32 v43, v0
	v_mov_b32_e32 v44, v0
	v_mov_b32_e32 v45, v0
	v_mov_b32_e32 v46, v0
	v_mov_b32_e32 v47, v0
	v_mov_b32_e32 v48, v0
	v_mov_b32_e32 v49, v0
	v_mov_b32_e32 v50, v0
	v_mov_b32_e32 v51, v0
	v_mov_b32_e32 v52, v0
	v_mov_b32_e32 v53, v0
	v_mov_b32_e32 v54, v0
	v_mov_b32_e32 v55, v0
	v_mov_b32_e32 v56, v0
	v_mov_b32_e32 v57, v0
	v_mov_b32_e32 v58, v0
	v_mov_b32_e32 v59, v0
	v_mov_b32_e32 v60, v0
	v_mov_b32_e32 v61, v0
	v_mov_b32_e32 v62, v0
	v_mov_b32_e32 v63, v0
	v_mov_b32_e32 v64, v0
	v_mov_b32_e32 v65, v0
	v_mov_b32_e32 v66, v0
	v_mov_b32_e32 v67, v0
	v_mov_b32_e32 v68, v0
	v_mov_b32_e32 v69, v0
	v_mov_b32_e32 v70, v0
	v_mov_b32_e32 v71, v0
	v_mov_b32_e32 v72, v0
	v_mov_b32_e32 v73, v0
	v_mov_b32_e32 v74, v0
	v_mov_b32_e32 v75, v0
	v_mov_b32_e32 v76, v0
	v_mov_b32_e32 v77, v0
	v_mov_b32_e32 v78, v0
	v_mov_b32_e32 v79, v0
	v_mov_b32_e32 v80, v0
	v_mov_b32_e32 v81, v0
	v_mov_b32_e32 v82, v0
	v_mov_b32_e32 v83, v0
	v_mov_b32_e32 v84, v0
	v_mov_b32_e32 v85, v0
	v_mov_b32_e32 v86, v0
	v_mov_b32_e32 v87, v0
	v_mov_b32_e32 v88, v0
	v_mov_b32_e32 v89, v0
	v_mov_b32_e32 v90, v0
	v_mov_b32_e32 v91, v0
	v_mov_b32_e32 v92, v0
	v_mov_b32_e32 v93, v0
	v_mov_b32_e32 v94, v0
	v_mov_b32_e32 v95, v0
	v_mov_b32_e32 v96, v0
	v_mov_b32_e32 v97, v0
	v_mov_b32_e32 v98, v0
	v_mov_b32_e32 v99, v0
	v_mov_b32_e32 v100, v0
	v_mov_b32_e32 v101, v0
	v_mov_b32_e32 v102, v0
	v_mov_b32_e32 v103, v0
	v_mov_b32_e32 v104, v0
	v_mov_b32_e32 v105, v0
	v_mov_b32_e32 v106, v0
	v_mov_b32_e32 v107, v0
	v_mov_b32_e32 v108, v0
	v_mov_b32_e32 v109, v0
	v_mov_b32_e32 v110, v0
	v_mov_b32_e32 v111, v0
	v_mov_b32_e32 v112, v0
	v_mov_b32_e32 v113, v0
	v_mov_b32_e32 v114, v0
	v_mov_b32_e32 v115, v0
	v_mov_b32_e32 v116, v0
	v_mov_b32_e32 v117, v0
	v_mov_b32_e32 v118, v0
	v_mov_b32_e32 v119, v0
	v_mov_b32_e32 v120, v0
	v_mov_b32_e32 v121, v0
	v_mov_b32_e32 v122, v0
	v_mov_b32_e32 v123, v0
	v_mov_b32_e32 v124, v0
	v_mov_b32_e32 v125, v0
	v_mov_b32_e32 v126, v0
	v_mov_b32_e32 v127, v0
